# loop-head code placement: the four GEMM K-loop heads aligned to 64 bytes (s_nop fill, executed once per tile)
# speedup vs baseline: 1.0180x; 1.0053x over previous
.Lgprio0:
	v_add_u32_e32 v236, 0x10000, v175
	v_add_u32_e32 v237, 0x14000, v175
	v_add_u32_e32 v238, 0x18000, v175
	v_add_u32_e32 v239, 0x1c000, v175
	.p2alignl 6, 3212836864

.Lgprio1:
	v_add_u32_e32 v236, 0x10000, v172
	v_add_u32_e32 v237, 0x14000, v172
	v_add_u32_e32 v238, 0x18000, v172
	v_add_u32_e32 v239, 0x1c000, v172
	.p2alignl 6, 3212836864

.Lgprio3:
	v_add_u32_e32 v236, 0x10000, v176
	v_add_u32_e32 v237, 0x14000, v176
	v_add_u32_e32 v238, 0x18000, v176
	v_add_u32_e32 v239, 0x1c000, v176
	.p2alignl 6, 3212836864
